# GDN recurrence: per-step output scaling folded into the output stage (LDS scale table), race-free
# speedup vs baseline: 1.2108x; 1.0015x over previous
; __device__ __forceinline__ int otid() { int t = threadIdx.x; asm volatile("" : "+v"(t)); return t; }
; __device__ __forceinline__ void gdn_item(const Params& p, int item, float* sm) {
;   const int b = item >> 5, h = (item >> 3) & 3, c0 = (item & 7) * 16;
;   const bf16_t* gp = (const bf16_t*)p.out;
;   const float* gg = (const float*)(p.ws + OFF_GG);
;   bf16_t* O = (bf16_t*)(p.ws + OFF_O);
;   constexpr int TC = 16;
;   constexpr int BUF = 2 * TC * 128 + TC * 16 + 2 * TC + TC * 16 + TC;
;   const int tid = otid(), lane = tid & 63, wave = tid >> 6;
;   const int sub = lane & 15, cw = wave * 4 + (lane >> 4);
;   const int ltt = tid >> 4, lseg = tid & 15;
;   float S[8];
; #pragma unroll
;   for (int i = 0; i < 8; i++) S[i] = 0.f;
;   const size_t rowb = (size_t)b * LP;
;   uint4 pq, pk; bf16_t pv; float pg = 0.f, pb = 0.f;
;     ...
;   __syncthreads();
;   GDN_LOAD(PADR)
;   GDN_STORE(0)
;   __syncthreads();
.Lgd_item:
	v_readlane_b32 s14, v244, 27
	v_readlane_b32 s8, v247, 3
	v_readlane_b32 s9, v247, 4
	v_readlane_b32 s4, v247, 1
	v_readlane_b32 s5, v247, 2
	v_and_b32_e32 v136, 15, v2
	v_lshrrev_b32_e32 v137, 4, v2
	s_lshr_b32 s10, s14, 5
	s_bfe_u32 s11, s14, 0x20003
	s_and_b32 s12, s14, 7
	s_lshl_b32 s12, s12, 5
	s_mul_i32 s13, s10, 0x2080
	s_add_i32 s13, s13, 0x70
	s_add_u32 s6, s8, 0x19c8c000
	s_addc_u32 s7, s9, 0
	s_add_u32 s8, s8, 0x19d90000
	s_addc_u32 s9, s9, 0
	v_lshlrev_b32_e32 v45, 4, v136
	v_lshlrev_b32_e32 v132, 6, v137
	v_add_u32_e32 v132, 16384, v132
	v_lshlrev_b32_e32 v128, 5, v2
	v_lshl_add_u32 v129, v136, 4, v137
	v_lshlrev_b32_e32 v129, 2, v129
	v_add_u32_e32 v129, 16384, v129
	v_lshlrev_b32_e32 v130, 2, v137
	v_add_u32_e32 v130, 17472, v130
	v_lshlrev_b32_e32 v131, 2, v2
	v_add_u32_e32 v131, 17472, v131
	v_lshlrev_b32_e32 v133, 2, v137
	v_add_u32_e32 v133, 17408, v133
	v_lshlrev_b32_e32 v134, 2, v136
	v_add_u32_e32 v134, 17408, v134
	v_lshlrev_b32_e32 v135, 2, v137
	v_add_u32_e32 v135, 18496, v135
	v_add_u32_e32 v138, s13, v137
	s_lshl_b32 s14, s11, 8
	v_lshl_add_u32 v139, v136, 4, s14
	s_movk_i32 s15, 0xc00
	v_mad_u32_u24 v24, v138, s15, v139
	s_add_i32 s14, s14, s12
	v_lshl_add_u32 v140, v136, 1, s14
	v_mad_u32_u24 v25, v138, s15, v140
	v_add_u32_e32 v25, 0x800, v25
	v_lshl_add_u32 v27, v138, 11, v140
	v_add_u32_e32 v27, 0x400, v27
	v_add_u32_e32 v141, s13, v136
	s_lshl_b32 s14, s11, 2
	v_lshl_add_u32 v26, v141, 5, s14
	v_mov_b32_e32 v12, 0
	v_mov_b32_e32 v13, 0
	v_mov_b32_e32 v14, 0
	v_mov_b32_e32 v15, 0
	v_mov_b32_e32 v16, 0
	v_mov_b32_e32 v17, 0
	v_mov_b32_e32 v18, 0
	v_mov_b32_e32 v19, 0
	s_barrier
	global_load_dwordx4 v[28:31], v24, s[4:5]
	global_load_dwordx4 v[32:35], v24, s[4:5] offset:1024
	global_load_ushort v36, v25, s[4:5]
	global_load_dword v37, v26, s[6:7]
	global_load_dword v38, v26, s[6:7] offset:16
	v_mov_b32_e32 v39, v128
	v_mov_b32_e32 v40, v129
	v_mov_b32_e32 v43, v133
	v_add_u32_e32 v142, 1088, v134
	s_waitcnt vmcnt(0)
	v_lshlrev_b32_e32 v48, 16, v28
	v_and_b32_e32 v49, 0xffff0000, v28
	v_lshlrev_b32_e32 v50, 16, v29
	v_and_b32_e32 v51, 0xffff0000, v29
	v_lshlrev_b32_e32 v52, 16, v30
	v_and_b32_e32 v53, 0xffff0000, v30
	v_lshlrev_b32_e32 v54, 16, v31
	v_and_b32_e32 v55, 0xffff0000, v31
	v_lshlrev_b32_e32 v56, 16, v32
	v_and_b32_e32 v57, 0xffff0000, v32
	v_lshlrev_b32_e32 v58, 16, v33
	v_and_b32_e32 v59, 0xffff0000, v33
	v_lshlrev_b32_e32 v60, 16, v34
	v_and_b32_e32 v61, 0xffff0000, v34
	v_lshlrev_b32_e32 v62, 16, v35
	v_and_b32_e32 v63, 0xffff0000, v35
	v_lshlrev_b32_e32 v64, 16, v36
	v_mov_b32_e32 v65, v37
	ds_write_b128 v39, v[48:51]
	ds_write_b128 v39, v[52:55] offset:16
	v_add_f32_dpp v65, v65, v65 row_shr:1 row_mask:0xf bank_mask:0xf bound_ctrl:1
	ds_write_b128 v39, v[56:59] offset:8192
	ds_write_b128 v39, v[60:63] offset:8208
	v_add_f32_dpp v65, v65, v65 row_shr:2 row_mask:0xf bank_mask:0xf bound_ctrl:1
	v_pk_mul_f32 v[66:67], v[48:49], v[56:57]
	v_pk_fma_f32 v[66:67], v[50:51], v[58:59], v[66:67]
	v_add_f32_dpp v65, v65, v65 row_shr:4 row_mask:0xf bank_mask:0xf bound_ctrl:1
	v_pk_fma_f32 v[66:67], v[52:53], v[60:61], v[66:67]
	v_pk_fma_f32 v[66:67], v[54:55], v[62:63], v[66:67]
	v_add_f32_dpp v65, v65, v65 row_shr:8 row_mask:0xf bank_mask:0xf bound_ctrl:1
	v_add_f32_e32 v68, v66, v67
	ds_write_b32 v40, v64
	v_max_f32_e32 v65, 0xc2a00000, v65
	v_add_f32_dpp v68, v68, v68 quad_perm:[1,0,3,2] row_mask:0xf bank_mask:0xf bound_ctrl:1
	v_mul_f32_e32 v65, 0x3fb8aa3b, v65
	s_nop 0
	v_add_f32_dpp v68, v68, v68 quad_perm:[2,3,0,1] row_mask:0xf bank_mask:0xf bound_ctrl:1
	v_exp_f32_e32 v69, v65
	v_exp_f32_e64 v70, -v65
	v_add_f32_dpp v68, v68, v68 row_half_mirror row_mask:0xf bank_mask:0xf bound_ctrl:1
	s_nop 1
	v_add_f32_dpp v68, v68, v68 row_mirror row_mask:0xf bank_mask:0xf bound_ctrl:1
	v_mul_f32_e32 v23, 0x3db504f3, v69
	v_mul_f32_e32 v21, v38, v70
	v_sub_f32_e32 v20, 0, v69
	ds_write_b32 v43, v68
	ds_write_b32 v142, v23
	s_add_u32 s4, s4, 0xc000
	s_addc_u32 s5, s5, 0
	s_add_u32 s6, s6, 0x200
	s_addc_u32 s7, s7, 0
	s_mov_b32 s0, 0
	s_mov_b32 s1, 0
	v_mov_b32_e32 v10, v45
	v_mov_b32_e32 v11, v132
	v_mov_b32_e32 v44, v134
	s_waitcnt lgkmcnt(0)
	s_barrier
	ds_read_b32 v22, v44
	ds_read_b128 v[88:91], v11 offset:0
	ds_read_b128 v[92:95], v11 offset:16
	ds_read_b128 v[96:99], v11 offset:32
	ds_read_b128 v[100:103], v11 offset:48
	ds_read_b128 v[48:51], v10 offset:8192
	ds_read_b128 v[52:55], v10 offset:8448
	ds_read_b128 v[56:59], v10
	ds_read_b128 v[60:63], v10 offset:256
	s_waitcnt lgkmcnt(8)
	v_mul_f32_e32 v22, 0x3d800000, v22

; __device__ __forceinline__ void gdn_item(const Params& p, int item, float* sm) {
;     ...
;       for (int t = 0; t < TC; t++) {
;         const float4 k0 = *(const float4*)(bk + t * 128 + sub * 4);
;         const float4 k1 = *(const float4*)(bk + t * 128 + 64 + sub * 4);
;         const float4 q0 = *(const float4*)(bq + t * 128 + sub * 4);
;         const float4 q1 = *(const float4*)(bq + t * 128 + 64 + sub * 4);
;         const float v = bv[t * 16 + cw];
;         const float g = bg[t], be = bg[TC + t];
;         const float qk = bo[TC * 16 + t];
;         float pa = k0.x * S[0] + k0.y * S[1];
;         float pb2 = k0.z * S[2] + k0.w * S[3];
;         float qa = q0.x * S[0] + q0.y * S[1];
;         float qb2 = q0.z * S[2] + q0.w * S[3];
;         pa += k1.x * S[4] + k1.y * S[5];
;         pb2 += k1.z * S[6] + k1.w * S[7];
;         qa += q1.x * S[4] + q1.y * S[5];
;         qb2 += q1.z * S[6] + q1.w * S[7];
;         const float ks = dpp_sum16(pa + pb2);
;         const float qs = dpp_sum16(qa + qb2);
;         const float coef = be * (v - g * ks);
;         const float oo = g * qs + coef * qk;
;         S[0] = g * S[0] + coef * k0.x; S[1] = g * S[1] + coef * k0.y; S[2] = g * S[2] + coef * k0.z; S[3] = g * S[3] + coef * k0.w;
;         S[4] = g * S[4] + coef * k1.x; S[5] = g * S[5] + coef * k1.y; S[6] = g * S[6] + coef * k1.z; S[7] = g * S[7] + coef * k1.w;
;         oreg[t] = oo * 0.08838834764831845f;
.Lgd_noload:
	s_waitcnt lgkmcnt(0)
	v_pk_mul_f32 v[120:121], v[12:13], v[48:49]
	v_pk_fma_f32 v[120:121], v[14:15], v[50:51], v[120:121]
	v_pk_fma_f32 v[120:121], v[16:17], v[52:53], v[120:121]
	v_pk_fma_f32 v[120:121], v[18:19], v[54:55], v[120:121]
	v_pk_mul_f32 v[122:123], v[12:13], v[56:57]
	v_add_f32_e32 v124, v120, v121
	v_pk_fma_f32 v[122:123], v[14:15], v[58:59], v[122:123]
	v_pk_fma_f32 v[122:123], v[16:17], v[60:61], v[122:123]
	v_add_f32_dpp v124, v124, v124 quad_perm:[1,0,3,2] row_mask:0xf bank_mask:0xf bound_ctrl:1
	v_pk_fma_f32 v[122:123], v[18:19], v[62:63], v[122:123]
	ds_read_b128 v[64:67], v10 offset:8704
	v_add_f32_dpp v124, v124, v124 quad_perm:[2,3,0,1] row_mask:0xf bank_mask:0xf bound_ctrl:1
	v_add_f32_e32 v104, v122, v123
	ds_read_b128 v[68:71], v10 offset:8960
	v_add_f32_dpp v124, v124, v124 row_half_mirror row_mask:0xf bank_mask:0xf bound_ctrl:1
	ds_read_b128 v[72:75], v10 offset:512
	ds_read_b128 v[76:79], v10 offset:768
	v_add_f32_dpp v124, v124, v124 row_mirror row_mask:0xf bank_mask:0xf bound_ctrl:1
	v_fmac_f32_dpp v88, v20, v124 row_newbcast:0 row_mask:0xf bank_mask:0xf
	v_mul_f32_dpp v126, v21, v88 row_newbcast:0 row_mask:0xf bank_mask:0xf
	v_pk_fma_f32 v[12:13], v[48:49], v[126:127], v[12:13] op_sel_hi:[1,0,1]
	v_pk_fma_f32 v[14:15], v[50:51], v[126:127], v[14:15] op_sel_hi:[1,0,1]
	v_pk_fma_f32 v[16:17], v[52:53], v[126:127], v[16:17] op_sel_hi:[1,0,1]
	v_pk_fma_f32 v[18:19], v[54:55], v[126:127], v[18:19] op_sel_hi:[1,0,1]
	v_fmac_f32_dpp v104, v22, v126 row_newbcast:0 row_mask:0xf bank_mask:0xf
	s_waitcnt lgkmcnt(0)
	v_pk_mul_f32 v[120:121], v[12:13], v[64:65]
	v_pk_fma_f32 v[120:121], v[14:15], v[66:67], v[120:121]
	v_pk_fma_f32 v[120:121], v[16:17], v[68:69], v[120:121]
	v_pk_fma_f32 v[120:121], v[18:19], v[70:71], v[120:121]
	v_pk_mul_f32 v[122:123], v[12:13], v[72:73]
	v_add_f32_e32 v124, v120, v121
	v_pk_fma_f32 v[122:123], v[14:15], v[74:75], v[122:123]
	v_pk_fma_f32 v[122:123], v[16:17], v[76:77], v[122:123]
	v_add_f32_dpp v124, v124, v124 quad_perm:[1,0,3,2] row_mask:0xf bank_mask:0xf bound_ctrl:1
	v_pk_fma_f32 v[122:123], v[18:19], v[78:79], v[122:123]
	ds_read_b128 v[48:51], v10 offset:9216
	v_add_f32_dpp v124, v124, v124 quad_perm:[2,3,0,1] row_mask:0xf bank_mask:0xf bound_ctrl:1
	v_add_f32_e32 v105, v122, v123
	ds_read_b128 v[52:55], v10 offset:9472
	v_add_f32_dpp v124, v124, v124 row_half_mirror row_mask:0xf bank_mask:0xf bound_ctrl:1
	ds_read_b128 v[56:59], v10 offset:1024
	ds_read_b128 v[60:63], v10 offset:1280
	v_add_f32_dpp v124, v124, v124 row_mirror row_mask:0xf bank_mask:0xf bound_ctrl:1
	v_fmac_f32_dpp v89, v20, v124 row_newbcast:1 row_mask:0xf bank_mask:0xf
	v_mul_f32_dpp v126, v21, v89 row_newbcast:1 row_mask:0xf bank_mask:0xf
	v_pk_fma_f32 v[12:13], v[64:65], v[126:127], v[12:13] op_sel_hi:[1,0,1]
	v_pk_fma_f32 v[14:15], v[66:67], v[126:127], v[14:15] op_sel_hi:[1,0,1]
	v_pk_fma_f32 v[16:17], v[68:69], v[126:127], v[16:17] op_sel_hi:[1,0,1]
	v_pk_fma_f32 v[18:19], v[70:71], v[126:127], v[18:19] op_sel_hi:[1,0,1]
	v_fmac_f32_dpp v105, v22, v126 row_newbcast:1 row_mask:0xf bank_mask:0xf
	s_waitcnt lgkmcnt(0)
	v_pk_mul_f32 v[120:121], v[12:13], v[48:49]
	v_pk_fma_f32 v[120:121], v[14:15], v[50:51], v[120:121]
	v_pk_fma_f32 v[120:121], v[16:17], v[52:53], v[120:121]
	v_pk_fma_f32 v[120:121], v[18:19], v[54:55], v[120:121]
	v_pk_mul_f32 v[122:123], v[12:13], v[56:57]
	v_add_f32_e32 v124, v120, v121
	v_pk_fma_f32 v[122:123], v[14:15], v[58:59], v[122:123]
	v_pk_fma_f32 v[122:123], v[16:17], v[60:61], v[122:123]
	v_add_f32_dpp v124, v124, v124 quad_perm:[1,0,3,2] row_mask:0xf bank_mask:0xf bound_ctrl:1
	v_pk_fma_f32 v[122:123], v[18:19], v[62:63], v[122:123]
	ds_read_b128 v[64:67], v10 offset:9728
	v_add_f32_dpp v124, v124, v124 quad_perm:[2,3,0,1] row_mask:0xf bank_mask:0xf bound_ctrl:1
	v_add_f32_e32 v106, v122, v123
	ds_read_b128 v[68:71], v10 offset:9984
	v_add_f32_dpp v124, v124, v124 row_half_mirror row_mask:0xf bank_mask:0xf bound_ctrl:1
	ds_read_b128 v[72:75], v10 offset:1536
	ds_read_b128 v[76:79], v10 offset:1792
	v_add_f32_dpp v124, v124, v124 row_mirror row_mask:0xf bank_mask:0xf bound_ctrl:1
	v_fmac_f32_dpp v90, v20, v124 row_newbcast:2 row_mask:0xf bank_mask:0xf
	v_mul_f32_dpp v126, v21, v90 row_newbcast:2 row_mask:0xf bank_mask:0xf
	v_pk_fma_f32 v[12:13], v[48:49], v[126:127], v[12:13] op_sel_hi:[1,0,1]
	v_pk_fma_f32 v[14:15], v[50:51], v[126:127], v[14:15] op_sel_hi:[1,0,1]
	v_pk_fma_f32 v[16:17], v[52:53], v[126:127], v[16:17] op_sel_hi:[1,0,1]
	v_pk_fma_f32 v[18:19], v[54:55], v[126:127], v[18:19] op_sel_hi:[1,0,1]
	v_fmac_f32_dpp v106, v22, v126 row_newbcast:2 row_mask:0xf bank_mask:0xf
	s_waitcnt lgkmcnt(0)
	v_pk_mul_f32 v[120:121], v[12:13], v[64:65]
	v_pk_fma_f32 v[120:121], v[14:15], v[66:67], v[120:121]
	v_pk_fma_f32 v[120:121], v[16:17], v[68:69], v[120:121]
	v_pk_fma_f32 v[120:121], v[18:19], v[70:71], v[120:121]
	v_pk_mul_f32 v[122:123], v[12:13], v[72:73]
	v_add_f32_e32 v124, v120, v121
	v_pk_fma_f32 v[122:123], v[14:15], v[74:75], v[122:123]
	v_pk_fma_f32 v[122:123], v[16:17], v[76:77], v[122:123]
	v_add_f32_dpp v124, v124, v124 quad_perm:[1,0,3,2] row_mask:0xf bank_mask:0xf bound_ctrl:1
	v_pk_fma_f32 v[122:123], v[18:19], v[78:79], v[122:123]
	ds_read_b128 v[48:51], v10 offset:10240
	v_add_f32_dpp v124, v124, v124 quad_perm:[2,3,0,1] row_mask:0xf bank_mask:0xf bound_ctrl:1
	v_add_f32_e32 v107, v122, v123
	ds_read_b128 v[52:55], v10 offset:10496
	v_add_f32_dpp v124, v124, v124 row_half_mirror row_mask:0xf bank_mask:0xf bound_ctrl:1
	ds_read_b128 v[56:59], v10 offset:2048
	ds_read_b128 v[60:63], v10 offset:2304
	v_add_f32_dpp v124, v124, v124 row_mirror row_mask:0xf bank_mask:0xf bound_ctrl:1
	v_fmac_f32_dpp v91, v20, v124 row_newbcast:3 row_mask:0xf bank_mask:0xf
	v_mul_f32_dpp v126, v21, v91 row_newbcast:3 row_mask:0xf bank_mask:0xf
	v_pk_fma_f32 v[12:13], v[64:65], v[126:127], v[12:13] op_sel_hi:[1,0,1]
	v_pk_fma_f32 v[14:15], v[66:67], v[126:127], v[14:15] op_sel_hi:[1,0,1]
	v_pk_fma_f32 v[16:17], v[68:69], v[126:127], v[16:17] op_sel_hi:[1,0,1]
	v_pk_fma_f32 v[18:19], v[70:71], v[126:127], v[18:19] op_sel_hi:[1,0,1]
	v_fmac_f32_dpp v107, v22, v126 row_newbcast:3 row_mask:0xf bank_mask:0xf
	s_waitcnt lgkmcnt(0)
; __device__ __forceinline__ void gdn_item(const Params& p, int item, float* sm) {
;     ...
;       for (int t = 0; t < TC; t++) {
;         const float4 k0 = *(const float4*)(bk + t * 128 + sub * 4);
;         const float4 k1 = *(const float4*)(bk + t * 128 + 64 + sub * 4);
;         const float4 q0 = *(const float4*)(bq + t * 128 + sub * 4);
;         const float4 q1 = *(const float4*)(bq + t * 128 + 64 + sub * 4);
;         const float v = bv[t * 16 + cw];
;         const float g = bg[t], be = bg[TC + t];
;         const float qk = bo[TC * 16 + t];
;         float pa = k0.x * S[0] + k0.y * S[1];
;         float pb2 = k0.z * S[2] + k0.w * S[3];
;         float qa = q0.x * S[0] + q0.y * S[1];
;         float qb2 = q0.z * S[2] + q0.w * S[3];
;         pa += k1.x * S[4] + k1.y * S[5];
;         pb2 += k1.z * S[6] + k1.w * S[7];
;         qa += q1.x * S[4] + q1.y * S[5];
;         qb2 += q1.z * S[6] + q1.w * S[7];
;         const float ks = dpp_sum16(pa + pb2);
;         const float qs = dpp_sum16(qa + qb2);
;         const float coef = be * (v - g * ks);
;         const float oo = g * qs + coef * qk;
;         S[0] = g * S[0] + coef * k0.x; S[1] = g * S[1] + coef * k0.y; S[2] = g * S[2] + coef * k0.z; S[3] = g * S[3] + coef * k0.w;
;         S[4] = g * S[4] + coef * k1.x; S[5] = g * S[5] + coef * k1.y; S[6] = g * S[6] + coef * k1.z; S[7] = g * S[7] + coef * k1.w;
;         oreg[t] = oo * 0.08838834764831845f;
	v_pk_mul_f32 v[120:121], v[12:13], v[48:49]
	v_pk_fma_f32 v[120:121], v[14:15], v[50:51], v[120:121]
	v_pk_fma_f32 v[120:121], v[16:17], v[52:53], v[120:121]
	v_pk_fma_f32 v[120:121], v[18:19], v[54:55], v[120:121]
	v_pk_mul_f32 v[122:123], v[12:13], v[56:57]
	v_add_f32_e32 v124, v120, v121
	v_pk_fma_f32 v[122:123], v[14:15], v[58:59], v[122:123]
	v_pk_fma_f32 v[122:123], v[16:17], v[60:61], v[122:123]
	v_add_f32_dpp v124, v124, v124 quad_perm:[1,0,3,2] row_mask:0xf bank_mask:0xf bound_ctrl:1
	v_pk_fma_f32 v[122:123], v[18:19], v[62:63], v[122:123]
	ds_read_b128 v[64:67], v10 offset:10752
	v_add_f32_dpp v124, v124, v124 quad_perm:[2,3,0,1] row_mask:0xf bank_mask:0xf bound_ctrl:1
	v_add_f32_e32 v108, v122, v123
	ds_read_b128 v[68:71], v10 offset:11008
	v_add_f32_dpp v124, v124, v124 row_half_mirror row_mask:0xf bank_mask:0xf bound_ctrl:1
	ds_read_b128 v[72:75], v10 offset:2560
	ds_read_b128 v[76:79], v10 offset:2816
	v_add_f32_dpp v124, v124, v124 row_mirror row_mask:0xf bank_mask:0xf bound_ctrl:1
	v_fmac_f32_dpp v92, v20, v124 row_newbcast:4 row_mask:0xf bank_mask:0xf
	v_mul_f32_dpp v126, v21, v92 row_newbcast:4 row_mask:0xf bank_mask:0xf
	v_pk_fma_f32 v[12:13], v[48:49], v[126:127], v[12:13] op_sel_hi:[1,0,1]
	v_pk_fma_f32 v[14:15], v[50:51], v[126:127], v[14:15] op_sel_hi:[1,0,1]
	v_pk_fma_f32 v[16:17], v[52:53], v[126:127], v[16:17] op_sel_hi:[1,0,1]
	v_pk_fma_f32 v[18:19], v[54:55], v[126:127], v[18:19] op_sel_hi:[1,0,1]
	v_fmac_f32_dpp v108, v22, v126 row_newbcast:4 row_mask:0xf bank_mask:0xf
	s_waitcnt lgkmcnt(0)
	v_pk_mul_f32 v[120:121], v[12:13], v[64:65]
	v_pk_fma_f32 v[120:121], v[14:15], v[66:67], v[120:121]
	v_pk_fma_f32 v[120:121], v[16:17], v[68:69], v[120:121]
	v_pk_fma_f32 v[120:121], v[18:19], v[70:71], v[120:121]
	v_pk_mul_f32 v[122:123], v[12:13], v[72:73]
	v_add_f32_e32 v124, v120, v121
	v_pk_fma_f32 v[122:123], v[14:15], v[74:75], v[122:123]
	v_pk_fma_f32 v[122:123], v[16:17], v[76:77], v[122:123]
	v_add_f32_dpp v124, v124, v124 quad_perm:[1,0,3,2] row_mask:0xf bank_mask:0xf bound_ctrl:1
	v_pk_fma_f32 v[122:123], v[18:19], v[78:79], v[122:123]
	ds_read_b128 v[48:51], v10 offset:11264
	v_add_f32_dpp v124, v124, v124 quad_perm:[2,3,0,1] row_mask:0xf bank_mask:0xf bound_ctrl:1
	v_add_f32_e32 v109, v122, v123
	ds_read_b128 v[52:55], v10 offset:11520
	v_add_f32_dpp v124, v124, v124 row_half_mirror row_mask:0xf bank_mask:0xf bound_ctrl:1
	ds_read_b128 v[56:59], v10 offset:3072
	ds_read_b128 v[60:63], v10 offset:3328
	v_add_f32_dpp v124, v124, v124 row_mirror row_mask:0xf bank_mask:0xf bound_ctrl:1
	v_fmac_f32_dpp v93, v20, v124 row_newbcast:5 row_mask:0xf bank_mask:0xf
	v_mul_f32_dpp v126, v21, v93 row_newbcast:5 row_mask:0xf bank_mask:0xf
	v_pk_fma_f32 v[12:13], v[64:65], v[126:127], v[12:13] op_sel_hi:[1,0,1]
	v_pk_fma_f32 v[14:15], v[66:67], v[126:127], v[14:15] op_sel_hi:[1,0,1]
	v_pk_fma_f32 v[16:17], v[68:69], v[126:127], v[16:17] op_sel_hi:[1,0,1]
	v_pk_fma_f32 v[18:19], v[70:71], v[126:127], v[18:19] op_sel_hi:[1,0,1]
	v_fmac_f32_dpp v109, v22, v126 row_newbcast:5 row_mask:0xf bank_mask:0xf
	s_waitcnt lgkmcnt(0)
	v_pk_mul_f32 v[120:121], v[12:13], v[48:49]
	v_pk_fma_f32 v[120:121], v[14:15], v[50:51], v[120:121]
	v_pk_fma_f32 v[120:121], v[16:17], v[52:53], v[120:121]
	v_pk_fma_f32 v[120:121], v[18:19], v[54:55], v[120:121]
	v_pk_mul_f32 v[122:123], v[12:13], v[56:57]
	v_add_f32_e32 v124, v120, v121
	v_pk_fma_f32 v[122:123], v[14:15], v[58:59], v[122:123]
	v_pk_fma_f32 v[122:123], v[16:17], v[60:61], v[122:123]
	v_add_f32_dpp v124, v124, v124 quad_perm:[1,0,3,2] row_mask:0xf bank_mask:0xf bound_ctrl:1
	v_pk_fma_f32 v[122:123], v[18:19], v[62:63], v[122:123]
	ds_read_b128 v[64:67], v10 offset:11776
	v_add_f32_dpp v124, v124, v124 quad_perm:[2,3,0,1] row_mask:0xf bank_mask:0xf bound_ctrl:1
	v_add_f32_e32 v110, v122, v123
	ds_read_b128 v[68:71], v10 offset:12032
	v_add_f32_dpp v124, v124, v124 row_half_mirror row_mask:0xf bank_mask:0xf bound_ctrl:1
	ds_read_b128 v[72:75], v10 offset:3584
	ds_read_b128 v[76:79], v10 offset:3840
	v_add_f32_dpp v124, v124, v124 row_mirror row_mask:0xf bank_mask:0xf bound_ctrl:1
	v_fmac_f32_dpp v94, v20, v124 row_newbcast:6 row_mask:0xf bank_mask:0xf
	v_mul_f32_dpp v126, v21, v94 row_newbcast:6 row_mask:0xf bank_mask:0xf
	v_pk_fma_f32 v[12:13], v[48:49], v[126:127], v[12:13] op_sel_hi:[1,0,1]
	v_pk_fma_f32 v[14:15], v[50:51], v[126:127], v[14:15] op_sel_hi:[1,0,1]
	v_pk_fma_f32 v[16:17], v[52:53], v[126:127], v[16:17] op_sel_hi:[1,0,1]
	v_pk_fma_f32 v[18:19], v[54:55], v[126:127], v[18:19] op_sel_hi:[1,0,1]
	v_fmac_f32_dpp v110, v22, v126 row_newbcast:6 row_mask:0xf bank_mask:0xf
	s_waitcnt lgkmcnt(0)
	v_pk_mul_f32 v[120:121], v[12:13], v[64:65]
	v_pk_fma_f32 v[120:121], v[14:15], v[66:67], v[120:121]
	v_pk_fma_f32 v[120:121], v[16:17], v[68:69], v[120:121]
	v_pk_fma_f32 v[120:121], v[18:19], v[70:71], v[120:121]
	v_pk_mul_f32 v[122:123], v[12:13], v[72:73]
	v_add_f32_e32 v124, v120, v121
	v_pk_fma_f32 v[122:123], v[14:15], v[74:75], v[122:123]
	v_pk_fma_f32 v[122:123], v[16:17], v[76:77], v[122:123]
	v_add_f32_dpp v124, v124, v124 quad_perm:[1,0,3,2] row_mask:0xf bank_mask:0xf bound_ctrl:1
	v_pk_fma_f32 v[122:123], v[18:19], v[78:79], v[122:123]
	ds_read_b128 v[48:51], v10 offset:12288
	v_add_f32_dpp v124, v124, v124 quad_perm:[2,3,0,1] row_mask:0xf bank_mask:0xf bound_ctrl:1
	v_add_f32_e32 v111, v122, v123
	ds_read_b128 v[52:55], v10 offset:12544
	v_add_f32_dpp v124, v124, v124 row_half_mirror row_mask:0xf bank_mask:0xf bound_ctrl:1
	ds_read_b128 v[56:59], v10 offset:4096
	ds_read_b128 v[60:63], v10 offset:4352
	v_add_f32_dpp v124, v124, v124 row_mirror row_mask:0xf bank_mask:0xf bound_ctrl:1
	v_fmac_f32_dpp v95, v20, v124 row_newbcast:7 row_mask:0xf bank_mask:0xf
	v_mul_f32_dpp v126, v21, v95 row_newbcast:7 row_mask:0xf bank_mask:0xf
	v_pk_fma_f32 v[12:13], v[64:65], v[126:127], v[12:13] op_sel_hi:[1,0,1]
	v_pk_fma_f32 v[14:15], v[66:67], v[126:127], v[14:15] op_sel_hi:[1,0,1]
	v_pk_fma_f32 v[16:17], v[68:69], v[126:127], v[16:17] op_sel_hi:[1,0,1]
	v_pk_fma_f32 v[18:19], v[70:71], v[126:127], v[18:19] op_sel_hi:[1,0,1]
	v_fmac_f32_dpp v111, v22, v126 row_newbcast:7 row_mask:0xf bank_mask:0xf
	s_waitcnt lgkmcnt(0)
; __device__ __forceinline__ void gdn_item(const Params& p, int item, float* sm) {
;     ...
;       for (int t = 0; t < TC; t++) {
;         const float4 k0 = *(const float4*)(bk + t * 128 + sub * 4);
;         const float4 k1 = *(const float4*)(bk + t * 128 + 64 + sub * 4);
;         const float4 q0 = *(const float4*)(bq + t * 128 + sub * 4);
;         const float4 q1 = *(const float4*)(bq + t * 128 + 64 + sub * 4);
;         const float v = bv[t * 16 + cw];
;         const float g = bg[t], be = bg[TC + t];
;         const float qk = bo[TC * 16 + t];
;         float pa = k0.x * S[0] + k0.y * S[1];
;         float pb2 = k0.z * S[2] + k0.w * S[3];
;         float qa = q0.x * S[0] + q0.y * S[1];
;         float qb2 = q0.z * S[2] + q0.w * S[3];
;         pa += k1.x * S[4] + k1.y * S[5];
;         pb2 += k1.z * S[6] + k1.w * S[7];
;         qa += q1.x * S[4] + q1.y * S[5];
;         qb2 += q1.z * S[6] + q1.w * S[7];
;         const float ks = dpp_sum16(pa + pb2);
;         const float qs = dpp_sum16(qa + qb2);
;         const float coef = be * (v - g * ks);
;         const float oo = g * qs + coef * qk;
;         S[0] = g * S[0] + coef * k0.x; S[1] = g * S[1] + coef * k0.y; S[2] = g * S[2] + coef * k0.z; S[3] = g * S[3] + coef * k0.w;
;         S[4] = g * S[4] + coef * k1.x; S[5] = g * S[5] + coef * k1.y; S[6] = g * S[6] + coef * k1.z; S[7] = g * S[7] + coef * k1.w;
;         oreg[t] = oo * 0.08838834764831845f;
	v_pk_mul_f32 v[120:121], v[12:13], v[48:49]
	v_pk_fma_f32 v[120:121], v[14:15], v[50:51], v[120:121]
	v_pk_fma_f32 v[120:121], v[16:17], v[52:53], v[120:121]
	v_pk_fma_f32 v[120:121], v[18:19], v[54:55], v[120:121]
	v_pk_mul_f32 v[122:123], v[12:13], v[56:57]
	v_add_f32_e32 v124, v120, v121
	v_pk_fma_f32 v[122:123], v[14:15], v[58:59], v[122:123]
	v_pk_fma_f32 v[122:123], v[16:17], v[60:61], v[122:123]
	v_add_f32_dpp v124, v124, v124 quad_perm:[1,0,3,2] row_mask:0xf bank_mask:0xf bound_ctrl:1
	v_pk_fma_f32 v[122:123], v[18:19], v[62:63], v[122:123]
	ds_read_b128 v[64:67], v10 offset:12800
	v_add_f32_dpp v124, v124, v124 quad_perm:[2,3,0,1] row_mask:0xf bank_mask:0xf bound_ctrl:1
	v_add_f32_e32 v112, v122, v123
	ds_read_b128 v[68:71], v10 offset:13056
	v_add_f32_dpp v124, v124, v124 row_half_mirror row_mask:0xf bank_mask:0xf bound_ctrl:1
	ds_read_b128 v[72:75], v10 offset:4608
	ds_read_b128 v[76:79], v10 offset:4864
	v_add_f32_dpp v124, v124, v124 row_mirror row_mask:0xf bank_mask:0xf bound_ctrl:1
	v_fmac_f32_dpp v96, v20, v124 row_newbcast:8 row_mask:0xf bank_mask:0xf
	v_mul_f32_dpp v126, v21, v96 row_newbcast:8 row_mask:0xf bank_mask:0xf
	v_pk_fma_f32 v[12:13], v[48:49], v[126:127], v[12:13] op_sel_hi:[1,0,1]
	v_pk_fma_f32 v[14:15], v[50:51], v[126:127], v[14:15] op_sel_hi:[1,0,1]
	v_pk_fma_f32 v[16:17], v[52:53], v[126:127], v[16:17] op_sel_hi:[1,0,1]
	v_pk_fma_f32 v[18:19], v[54:55], v[126:127], v[18:19] op_sel_hi:[1,0,1]
	v_fmac_f32_dpp v112, v22, v126 row_newbcast:8 row_mask:0xf bank_mask:0xf
	s_waitcnt lgkmcnt(0)
	v_pk_mul_f32 v[120:121], v[12:13], v[64:65]
	v_pk_fma_f32 v[120:121], v[14:15], v[66:67], v[120:121]
	v_pk_fma_f32 v[120:121], v[16:17], v[68:69], v[120:121]
	v_pk_fma_f32 v[120:121], v[18:19], v[70:71], v[120:121]
	v_pk_mul_f32 v[122:123], v[12:13], v[72:73]
	v_add_f32_e32 v124, v120, v121
	v_pk_fma_f32 v[122:123], v[14:15], v[74:75], v[122:123]
	v_pk_fma_f32 v[122:123], v[16:17], v[76:77], v[122:123]
	v_add_f32_dpp v124, v124, v124 quad_perm:[1,0,3,2] row_mask:0xf bank_mask:0xf bound_ctrl:1
	v_pk_fma_f32 v[122:123], v[18:19], v[78:79], v[122:123]
	ds_read_b128 v[48:51], v10 offset:13312
	v_add_f32_dpp v124, v124, v124 quad_perm:[2,3,0,1] row_mask:0xf bank_mask:0xf bound_ctrl:1
	v_add_f32_e32 v113, v122, v123
	ds_read_b128 v[52:55], v10 offset:13568
	v_add_f32_dpp v124, v124, v124 row_half_mirror row_mask:0xf bank_mask:0xf bound_ctrl:1
	ds_read_b128 v[56:59], v10 offset:5120
	ds_read_b128 v[60:63], v10 offset:5376
	v_add_f32_dpp v124, v124, v124 row_mirror row_mask:0xf bank_mask:0xf bound_ctrl:1
	v_fmac_f32_dpp v97, v20, v124 row_newbcast:9 row_mask:0xf bank_mask:0xf
	v_mul_f32_dpp v126, v21, v97 row_newbcast:9 row_mask:0xf bank_mask:0xf
	v_pk_fma_f32 v[12:13], v[64:65], v[126:127], v[12:13] op_sel_hi:[1,0,1]
	v_pk_fma_f32 v[14:15], v[66:67], v[126:127], v[14:15] op_sel_hi:[1,0,1]
	v_pk_fma_f32 v[16:17], v[68:69], v[126:127], v[16:17] op_sel_hi:[1,0,1]
	v_pk_fma_f32 v[18:19], v[70:71], v[126:127], v[18:19] op_sel_hi:[1,0,1]
	v_fmac_f32_dpp v113, v22, v126 row_newbcast:9 row_mask:0xf bank_mask:0xf
	s_waitcnt lgkmcnt(0)
	v_pk_mul_f32 v[120:121], v[12:13], v[48:49]
	v_pk_fma_f32 v[120:121], v[14:15], v[50:51], v[120:121]
	v_pk_fma_f32 v[120:121], v[16:17], v[52:53], v[120:121]
	v_pk_fma_f32 v[120:121], v[18:19], v[54:55], v[120:121]
	v_pk_mul_f32 v[122:123], v[12:13], v[56:57]
	v_add_f32_e32 v124, v120, v121
	v_pk_fma_f32 v[122:123], v[14:15], v[58:59], v[122:123]
	v_pk_fma_f32 v[122:123], v[16:17], v[60:61], v[122:123]
	v_add_f32_dpp v124, v124, v124 quad_perm:[1,0,3,2] row_mask:0xf bank_mask:0xf bound_ctrl:1
	v_pk_fma_f32 v[122:123], v[18:19], v[62:63], v[122:123]
	ds_read_b128 v[64:67], v10 offset:13824
	v_add_f32_dpp v124, v124, v124 quad_perm:[2,3,0,1] row_mask:0xf bank_mask:0xf bound_ctrl:1
	v_add_f32_e32 v114, v122, v123
	ds_read_b128 v[68:71], v10 offset:14080
	v_add_f32_dpp v124, v124, v124 row_half_mirror row_mask:0xf bank_mask:0xf bound_ctrl:1
	ds_read_b128 v[72:75], v10 offset:5632
	ds_read_b128 v[76:79], v10 offset:5888
	v_add_f32_dpp v124, v124, v124 row_mirror row_mask:0xf bank_mask:0xf bound_ctrl:1
	v_fmac_f32_dpp v98, v20, v124 row_newbcast:10 row_mask:0xf bank_mask:0xf
	v_mul_f32_dpp v126, v21, v98 row_newbcast:10 row_mask:0xf bank_mask:0xf
	v_pk_fma_f32 v[12:13], v[48:49], v[126:127], v[12:13] op_sel_hi:[1,0,1]
	v_pk_fma_f32 v[14:15], v[50:51], v[126:127], v[14:15] op_sel_hi:[1,0,1]
	v_pk_fma_f32 v[16:17], v[52:53], v[126:127], v[16:17] op_sel_hi:[1,0,1]
	v_pk_fma_f32 v[18:19], v[54:55], v[126:127], v[18:19] op_sel_hi:[1,0,1]
	v_fmac_f32_dpp v114, v22, v126 row_newbcast:10 row_mask:0xf bank_mask:0xf
	s_waitcnt lgkmcnt(0)
	v_pk_mul_f32 v[120:121], v[12:13], v[64:65]
	v_pk_fma_f32 v[120:121], v[14:15], v[66:67], v[120:121]
	v_pk_fma_f32 v[120:121], v[16:17], v[68:69], v[120:121]
	v_pk_fma_f32 v[120:121], v[18:19], v[70:71], v[120:121]
	v_pk_mul_f32 v[122:123], v[12:13], v[72:73]
	v_add_f32_e32 v124, v120, v121
	v_pk_fma_f32 v[122:123], v[14:15], v[74:75], v[122:123]
	v_pk_fma_f32 v[122:123], v[16:17], v[76:77], v[122:123]
	v_add_f32_dpp v124, v124, v124 quad_perm:[1,0,3,2] row_mask:0xf bank_mask:0xf bound_ctrl:1
	v_pk_fma_f32 v[122:123], v[18:19], v[78:79], v[122:123]
	ds_read_b128 v[48:51], v10 offset:14336
	v_add_f32_dpp v124, v124, v124 quad_perm:[2,3,0,1] row_mask:0xf bank_mask:0xf bound_ctrl:1
	v_add_f32_e32 v115, v122, v123
	ds_read_b128 v[52:55], v10 offset:14592
	v_add_f32_dpp v124, v124, v124 row_half_mirror row_mask:0xf bank_mask:0xf bound_ctrl:1
	ds_read_b128 v[56:59], v10 offset:6144
	ds_read_b128 v[60:63], v10 offset:6400
	v_add_f32_dpp v124, v124, v124 row_mirror row_mask:0xf bank_mask:0xf bound_ctrl:1
	v_fmac_f32_dpp v99, v20, v124 row_newbcast:11 row_mask:0xf bank_mask:0xf
	v_mul_f32_dpp v126, v21, v99 row_newbcast:11 row_mask:0xf bank_mask:0xf
	v_pk_fma_f32 v[12:13], v[64:65], v[126:127], v[12:13] op_sel_hi:[1,0,1]
	v_pk_fma_f32 v[14:15], v[66:67], v[126:127], v[14:15] op_sel_hi:[1,0,1]
	v_pk_fma_f32 v[16:17], v[68:69], v[126:127], v[16:17] op_sel_hi:[1,0,1]
	v_pk_fma_f32 v[18:19], v[70:71], v[126:127], v[18:19] op_sel_hi:[1,0,1]
	v_fmac_f32_dpp v115, v22, v126 row_newbcast:11 row_mask:0xf bank_mask:0xf
	s_waitcnt lgkmcnt(0)
; __device__ __forceinline__ void gdn_item(const Params& p, int item, float* sm) {
;     ...
;       for (int t = 0; t < TC; t++) {
;         const float4 k0 = *(const float4*)(bk + t * 128 + sub * 4);
;         const float4 k1 = *(const float4*)(bk + t * 128 + 64 + sub * 4);
;         const float4 q0 = *(const float4*)(bq + t * 128 + sub * 4);
;         const float4 q1 = *(const float4*)(bq + t * 128 + 64 + sub * 4);
;         const float v = bv[t * 16 + cw];
;         const float g = bg[t], be = bg[TC + t];
;         const float qk = bo[TC * 16 + t];
;         float pa = k0.x * S[0] + k0.y * S[1];
;         float pb2 = k0.z * S[2] + k0.w * S[3];
;         float qa = q0.x * S[0] + q0.y * S[1];
;         float qb2 = q0.z * S[2] + q0.w * S[3];
;         pa += k1.x * S[4] + k1.y * S[5];
;         pb2 += k1.z * S[6] + k1.w * S[7];
;         qa += q1.x * S[4] + q1.y * S[5];
;         qb2 += q1.z * S[6] + q1.w * S[7];
;         const float ks = dpp_sum16(pa + pb2);
;         const float qs = dpp_sum16(qa + qb2);
;         const float coef = be * (v - g * ks);
;         const float oo = g * qs + coef * qk;
;         S[0] = g * S[0] + coef * k0.x; S[1] = g * S[1] + coef * k0.y; S[2] = g * S[2] + coef * k0.z; S[3] = g * S[3] + coef * k0.w;
;         S[4] = g * S[4] + coef * k1.x; S[5] = g * S[5] + coef * k1.y; S[6] = g * S[6] + coef * k1.z; S[7] = g * S[7] + coef * k1.w;
;         oreg[t] = oo * 0.08838834764831845f;
	v_pk_mul_f32 v[120:121], v[12:13], v[48:49]
	v_pk_fma_f32 v[120:121], v[14:15], v[50:51], v[120:121]
	v_pk_fma_f32 v[120:121], v[16:17], v[52:53], v[120:121]
	v_pk_fma_f32 v[120:121], v[18:19], v[54:55], v[120:121]
	v_pk_mul_f32 v[122:123], v[12:13], v[56:57]
	v_add_f32_e32 v124, v120, v121
	v_pk_fma_f32 v[122:123], v[14:15], v[58:59], v[122:123]
	v_pk_fma_f32 v[122:123], v[16:17], v[60:61], v[122:123]
	v_add_f32_dpp v124, v124, v124 quad_perm:[1,0,3,2] row_mask:0xf bank_mask:0xf bound_ctrl:1
	v_pk_fma_f32 v[122:123], v[18:19], v[62:63], v[122:123]
	ds_read_b128 v[64:67], v10 offset:14848
	v_add_f32_dpp v124, v124, v124 quad_perm:[2,3,0,1] row_mask:0xf bank_mask:0xf bound_ctrl:1
	v_add_f32_e32 v116, v122, v123
	ds_read_b128 v[68:71], v10 offset:15104
	v_add_f32_dpp v124, v124, v124 row_half_mirror row_mask:0xf bank_mask:0xf bound_ctrl:1
	ds_read_b128 v[72:75], v10 offset:6656
	ds_read_b128 v[76:79], v10 offset:6912
	v_add_f32_dpp v124, v124, v124 row_mirror row_mask:0xf bank_mask:0xf bound_ctrl:1
	v_fmac_f32_dpp v100, v20, v124 row_newbcast:12 row_mask:0xf bank_mask:0xf
	v_mul_f32_dpp v126, v21, v100 row_newbcast:12 row_mask:0xf bank_mask:0xf
	v_pk_fma_f32 v[12:13], v[48:49], v[126:127], v[12:13] op_sel_hi:[1,0,1]
	v_pk_fma_f32 v[14:15], v[50:51], v[126:127], v[14:15] op_sel_hi:[1,0,1]
	v_pk_fma_f32 v[16:17], v[52:53], v[126:127], v[16:17] op_sel_hi:[1,0,1]
	v_pk_fma_f32 v[18:19], v[54:55], v[126:127], v[18:19] op_sel_hi:[1,0,1]
	v_fmac_f32_dpp v116, v22, v126 row_newbcast:12 row_mask:0xf bank_mask:0xf
	s_waitcnt lgkmcnt(0)
	v_pk_mul_f32 v[120:121], v[12:13], v[64:65]
	v_pk_fma_f32 v[120:121], v[14:15], v[66:67], v[120:121]
	v_pk_fma_f32 v[120:121], v[16:17], v[68:69], v[120:121]
	v_pk_fma_f32 v[120:121], v[18:19], v[70:71], v[120:121]
	v_pk_mul_f32 v[122:123], v[12:13], v[72:73]
	v_add_f32_e32 v124, v120, v121
	v_pk_fma_f32 v[122:123], v[14:15], v[74:75], v[122:123]
	v_pk_fma_f32 v[122:123], v[16:17], v[76:77], v[122:123]
	v_add_f32_dpp v124, v124, v124 quad_perm:[1,0,3,2] row_mask:0xf bank_mask:0xf bound_ctrl:1
	v_pk_fma_f32 v[122:123], v[18:19], v[78:79], v[122:123]
	ds_read_b128 v[48:51], v10 offset:15360
	v_add_f32_dpp v124, v124, v124 quad_perm:[2,3,0,1] row_mask:0xf bank_mask:0xf bound_ctrl:1
	v_add_f32_e32 v117, v122, v123
	ds_read_b128 v[52:55], v10 offset:15616
	v_add_f32_dpp v124, v124, v124 row_half_mirror row_mask:0xf bank_mask:0xf bound_ctrl:1
	ds_read_b128 v[56:59], v10 offset:7168
	ds_read_b128 v[60:63], v10 offset:7424
	v_add_f32_dpp v124, v124, v124 row_mirror row_mask:0xf bank_mask:0xf bound_ctrl:1
	v_fmac_f32_dpp v101, v20, v124 row_newbcast:13 row_mask:0xf bank_mask:0xf
	v_mul_f32_dpp v126, v21, v101 row_newbcast:13 row_mask:0xf bank_mask:0xf
	v_pk_fma_f32 v[12:13], v[64:65], v[126:127], v[12:13] op_sel_hi:[1,0,1]
	v_pk_fma_f32 v[14:15], v[66:67], v[126:127], v[14:15] op_sel_hi:[1,0,1]
	v_pk_fma_f32 v[16:17], v[68:69], v[126:127], v[16:17] op_sel_hi:[1,0,1]
	v_pk_fma_f32 v[18:19], v[70:71], v[126:127], v[18:19] op_sel_hi:[1,0,1]
	v_fmac_f32_dpp v117, v22, v126 row_newbcast:13 row_mask:0xf bank_mask:0xf
	s_waitcnt lgkmcnt(0)
	v_pk_mul_f32 v[120:121], v[12:13], v[48:49]
	v_pk_fma_f32 v[120:121], v[14:15], v[50:51], v[120:121]
	v_pk_fma_f32 v[120:121], v[16:17], v[52:53], v[120:121]
	v_pk_fma_f32 v[120:121], v[18:19], v[54:55], v[120:121]
	v_pk_mul_f32 v[122:123], v[12:13], v[56:57]
	v_add_f32_e32 v124, v120, v121
	v_pk_fma_f32 v[122:123], v[14:15], v[58:59], v[122:123]
	v_pk_fma_f32 v[122:123], v[16:17], v[60:61], v[122:123]
	v_add_f32_dpp v124, v124, v124 quad_perm:[1,0,3,2] row_mask:0xf bank_mask:0xf bound_ctrl:1
	v_pk_fma_f32 v[122:123], v[18:19], v[62:63], v[122:123]
	ds_read_b128 v[64:67], v10 offset:15872
	v_add_f32_dpp v124, v124, v124 quad_perm:[2,3,0,1] row_mask:0xf bank_mask:0xf bound_ctrl:1
	v_add_f32_e32 v118, v122, v123
	ds_read_b128 v[68:71], v10 offset:16128
	v_add_f32_dpp v124, v124, v124 row_half_mirror row_mask:0xf bank_mask:0xf bound_ctrl:1
	ds_read_b128 v[72:75], v10 offset:7680
	ds_read_b128 v[76:79], v10 offset:7936
	v_add_f32_dpp v124, v124, v124 row_mirror row_mask:0xf bank_mask:0xf bound_ctrl:1
	v_fmac_f32_dpp v102, v20, v124 row_newbcast:14 row_mask:0xf bank_mask:0xf
	v_mul_f32_dpp v126, v21, v102 row_newbcast:14 row_mask:0xf bank_mask:0xf
	v_pk_fma_f32 v[12:13], v[48:49], v[126:127], v[12:13] op_sel_hi:[1,0,1]
	v_pk_fma_f32 v[14:15], v[50:51], v[126:127], v[14:15] op_sel_hi:[1,0,1]
	v_pk_fma_f32 v[16:17], v[52:53], v[126:127], v[16:17] op_sel_hi:[1,0,1]
	v_pk_fma_f32 v[18:19], v[54:55], v[126:127], v[18:19] op_sel_hi:[1,0,1]
	v_fmac_f32_dpp v118, v22, v126 row_newbcast:14 row_mask:0xf bank_mask:0xf
	s_waitcnt lgkmcnt(0)
; __device__ __forceinline__ void gdn_item(const Params& p, int item, float* sm) {
;     ...
;       for (int t = 0; t < TC; t++) {
;         const float4 k0 = *(const float4*)(bk + t * 128 + sub * 4);
;         const float4 k1 = *(const float4*)(bk + t * 128 + 64 + sub * 4);
;         const float4 q0 = *(const float4*)(bq + t * 128 + sub * 4);
;         const float4 q1 = *(const float4*)(bq + t * 128 + 64 + sub * 4);
;         const float v = bv[t * 16 + cw];
;         const float g = bg[t], be = bg[TC + t];
;         const float qk = bo[TC * 16 + t];
;         float pa = k0.x * S[0] + k0.y * S[1];
;         float pb2 = k0.z * S[2] + k0.w * S[3];
;         float qa = q0.x * S[0] + q0.y * S[1];
;         float qb2 = q0.z * S[2] + q0.w * S[3];
;         pa += k1.x * S[4] + k1.y * S[5];
;         pb2 += k1.z * S[6] + k1.w * S[7];
;         qa += q1.x * S[4] + q1.y * S[5];
;         qb2 += q1.z * S[6] + q1.w * S[7];
;         const float ks = dpp_sum16(pa + pb2);
;         const float qs = dpp_sum16(qa + qb2);
;         const float coef = be * (v - g * ks);
;         const float oo = g * qs + coef * qk;
;         S[0] = g * S[0] + coef * k0.x; S[1] = g * S[1] + coef * k0.y; S[2] = g * S[2] + coef * k0.z; S[3] = g * S[3] + coef * k0.w;
;         S[4] = g * S[4] + coef * k1.x; S[5] = g * S[5] + coef * k1.y; S[6] = g * S[6] + coef * k1.z; S[7] = g * S[7] + coef * k1.w;
;         oreg[t] = oo * 0.08838834764831845f;
;       }
;       if (sub == 0) {
; #pragma unroll
;         for (int t = 0; t < TC; t++) bo[t * 16 + cw] = oreg[t];
	v_pk_mul_f32 v[120:121], v[12:13], v[64:65]
	v_pk_fma_f32 v[120:121], v[14:15], v[66:67], v[120:121]
	v_pk_fma_f32 v[120:121], v[16:17], v[68:69], v[120:121]
	v_pk_fma_f32 v[120:121], v[18:19], v[70:71], v[120:121]
	v_pk_mul_f32 v[122:123], v[12:13], v[72:73]
	v_add_f32_e32 v124, v120, v121
	v_pk_fma_f32 v[122:123], v[14:15], v[74:75], v[122:123]
	v_pk_fma_f32 v[122:123], v[16:17], v[76:77], v[122:123]
	v_add_f32_dpp v124, v124, v124 quad_perm:[1,0,3,2] row_mask:0xf bank_mask:0xf bound_ctrl:1
	v_pk_fma_f32 v[122:123], v[18:19], v[78:79], v[122:123]
	s_nop 0
	v_add_f32_dpp v124, v124, v124 quad_perm:[2,3,0,1] row_mask:0xf bank_mask:0xf bound_ctrl:1
	v_add_f32_e32 v119, v122, v123
	s_nop 0
	v_add_f32_dpp v124, v124, v124 row_half_mirror row_mask:0xf bank_mask:0xf bound_ctrl:1
	s_nop 1
	v_add_f32_dpp v124, v124, v124 row_mirror row_mask:0xf bank_mask:0xf bound_ctrl:1
	v_fmac_f32_dpp v103, v20, v124 row_newbcast:15 row_mask:0xf bank_mask:0xf
	v_mul_f32_dpp v126, v21, v103 row_newbcast:15 row_mask:0xf bank_mask:0xf
	v_pk_fma_f32 v[12:13], v[64:65], v[126:127], v[12:13] op_sel_hi:[1,0,1]
	v_pk_fma_f32 v[14:15], v[66:67], v[126:127], v[14:15] op_sel_hi:[1,0,1]
	v_pk_fma_f32 v[16:17], v[68:69], v[126:127], v[16:17] op_sel_hi:[1,0,1]
	v_pk_fma_f32 v[18:19], v[70:71], v[126:127], v[18:19] op_sel_hi:[1,0,1]
	v_fmac_f32_dpp v119, v22, v126 row_newbcast:15 row_mask:0xf bank_mask:0xf
	v_mov_b32_dpp v126, v20 row_newbcast:15 row_mask:0xf bank_mask:0xf
	v_add_f32_dpp v104, v104, v104 quad_perm:[1,0,3,2] row_mask:0xf bank_mask:0xf bound_ctrl:1
	v_add_f32_dpp v105, v105, v105 quad_perm:[1,0,3,2] row_mask:0xf bank_mask:0xf bound_ctrl:1
	v_add_f32_dpp v106, v106, v106 quad_perm:[1,0,3,2] row_mask:0xf bank_mask:0xf bound_ctrl:1
	v_add_f32_dpp v107, v107, v107 quad_perm:[1,0,3,2] row_mask:0xf bank_mask:0xf bound_ctrl:1
	v_add_f32_dpp v108, v108, v108 quad_perm:[1,0,3,2] row_mask:0xf bank_mask:0xf bound_ctrl:1
	v_add_f32_dpp v109, v109, v109 quad_perm:[1,0,3,2] row_mask:0xf bank_mask:0xf bound_ctrl:1
	v_add_f32_dpp v110, v110, v110 quad_perm:[1,0,3,2] row_mask:0xf bank_mask:0xf bound_ctrl:1
	v_add_f32_dpp v111, v111, v111 quad_perm:[1,0,3,2] row_mask:0xf bank_mask:0xf bound_ctrl:1
	v_add_f32_dpp v112, v112, v112 quad_perm:[1,0,3,2] row_mask:0xf bank_mask:0xf bound_ctrl:1
	v_add_f32_dpp v113, v113, v113 quad_perm:[1,0,3,2] row_mask:0xf bank_mask:0xf bound_ctrl:1
	v_add_f32_dpp v114, v114, v114 quad_perm:[1,0,3,2] row_mask:0xf bank_mask:0xf bound_ctrl:1
	v_add_f32_dpp v115, v115, v115 quad_perm:[1,0,3,2] row_mask:0xf bank_mask:0xf bound_ctrl:1
	v_add_f32_dpp v116, v116, v116 quad_perm:[1,0,3,2] row_mask:0xf bank_mask:0xf bound_ctrl:1
	v_add_f32_dpp v117, v117, v117 quad_perm:[1,0,3,2] row_mask:0xf bank_mask:0xf bound_ctrl:1
	v_add_f32_dpp v118, v118, v118 quad_perm:[1,0,3,2] row_mask:0xf bank_mask:0xf bound_ctrl:1
	v_add_f32_dpp v119, v119, v119 quad_perm:[1,0,3,2] row_mask:0xf bank_mask:0xf bound_ctrl:1
	v_pk_mul_f32 v[12:13], v[12:13], v[126:127] op_sel_hi:[1,0] neg_lo:[0,1] neg_hi:[0,1]
	v_pk_mul_f32 v[14:15], v[14:15], v[126:127] op_sel_hi:[1,0] neg_lo:[0,1] neg_hi:[0,1]
	v_pk_mul_f32 v[16:17], v[16:17], v[126:127] op_sel_hi:[1,0] neg_lo:[0,1] neg_hi:[0,1]
	v_pk_mul_f32 v[18:19], v[18:19], v[126:127] op_sel_hi:[1,0] neg_lo:[0,1] neg_hi:[0,1]
	v_add_f32_dpp v104, v104, v104 quad_perm:[2,3,0,1] row_mask:0xf bank_mask:0xf bound_ctrl:1
	v_add_f32_dpp v105, v105, v105 quad_perm:[2,3,0,1] row_mask:0xf bank_mask:0xf bound_ctrl:1
	v_add_f32_dpp v106, v106, v106 quad_perm:[2,3,0,1] row_mask:0xf bank_mask:0xf bound_ctrl:1
	v_add_f32_dpp v107, v107, v107 quad_perm:[2,3,0,1] row_mask:0xf bank_mask:0xf bound_ctrl:1
	v_add_f32_dpp v108, v108, v108 quad_perm:[2,3,0,1] row_mask:0xf bank_mask:0xf bound_ctrl:1
	v_add_f32_dpp v109, v109, v109 quad_perm:[2,3,0,1] row_mask:0xf bank_mask:0xf bound_ctrl:1
	v_add_f32_dpp v110, v110, v110 quad_perm:[2,3,0,1] row_mask:0xf bank_mask:0xf bound_ctrl:1
	v_add_f32_dpp v111, v111, v111 quad_perm:[2,3,0,1] row_mask:0xf bank_mask:0xf bound_ctrl:1
	v_add_f32_dpp v112, v112, v112 quad_perm:[2,3,0,1] row_mask:0xf bank_mask:0xf bound_ctrl:1
	v_add_f32_dpp v113, v113, v113 quad_perm:[2,3,0,1] row_mask:0xf bank_mask:0xf bound_ctrl:1
	v_add_f32_dpp v114, v114, v114 quad_perm:[2,3,0,1] row_mask:0xf bank_mask:0xf bound_ctrl:1
	v_add_f32_dpp v115, v115, v115 quad_perm:[2,3,0,1] row_mask:0xf bank_mask:0xf bound_ctrl:1
	v_add_f32_dpp v116, v116, v116 quad_perm:[2,3,0,1] row_mask:0xf bank_mask:0xf bound_ctrl:1
	v_add_f32_dpp v117, v117, v117 quad_perm:[2,3,0,1] row_mask:0xf bank_mask:0xf bound_ctrl:1
	v_add_f32_dpp v118, v118, v118 quad_perm:[2,3,0,1] row_mask:0xf bank_mask:0xf bound_ctrl:1
	v_add_f32_dpp v119, v119, v119 quad_perm:[2,3,0,1] row_mask:0xf bank_mask:0xf bound_ctrl:1
	v_add_f32_dpp v104, v104, v104 row_half_mirror row_mask:0xf bank_mask:0xf bound_ctrl:1
	v_add_f32_dpp v105, v105, v105 row_half_mirror row_mask:0xf bank_mask:0xf bound_ctrl:1
	v_add_f32_dpp v106, v106, v106 row_half_mirror row_mask:0xf bank_mask:0xf bound_ctrl:1
	v_add_f32_dpp v107, v107, v107 row_half_mirror row_mask:0xf bank_mask:0xf bound_ctrl:1
	v_add_f32_dpp v108, v108, v108 row_half_mirror row_mask:0xf bank_mask:0xf bound_ctrl:1
	v_add_f32_dpp v109, v109, v109 row_half_mirror row_mask:0xf bank_mask:0xf bound_ctrl:1
	v_add_f32_dpp v110, v110, v110 row_half_mirror row_mask:0xf bank_mask:0xf bound_ctrl:1
	v_add_f32_dpp v111, v111, v111 row_half_mirror row_mask:0xf bank_mask:0xf bound_ctrl:1
	v_add_f32_dpp v112, v112, v112 row_half_mirror row_mask:0xf bank_mask:0xf bound_ctrl:1
; __device__ __forceinline__ void gdn_item(const Params& p, int item, float* sm) {
;     ...
;         const float ks = dpp_sum16(pa + pb2);
;         const float qs = dpp_sum16(qa + qb2);
;         const float coef = be * (v - g * ks);
;         const float oo = g * qs + coef * qk;
;         S[0] = g * S[0] + coef * k0.x; S[1] = g * S[1] + coef * k0.y; S[2] = g * S[2] + coef * k0.z; S[3] = g * S[3] + coef * k0.w;
;         S[4] = g * S[4] + coef * k1.x; S[5] = g * S[5] + coef * k1.y; S[6] = g * S[6] + coef * k1.z; S[7] = g * S[7] + coef * k1.w;
;         oreg[t] = oo * 0.08838834764831845f;
;       }
;       if (sub == 0) {
; #pragma unroll
;         for (int t = 0; t < TC; t++) bo[t * 16 + cw] = oreg[t];
;       }
;     }
;     if (ch + 1 < NCH) GDN_STORE(bi ^ 1)
;     __syncthreads();
;     {
;       const float ov = sm[bi * BUF + 2 * TC * 128 + TC * 16 + 2 * TC + ltt * 16 + lseg];
;       O[(rowb + t0 + ltt) * D + 512 + h * 128 + c0 + lseg] = f2bf(ov);
	v_add_f32_dpp v113, v113, v113 row_half_mirror row_mask:0xf bank_mask:0xf bound_ctrl:1
	v_add_f32_dpp v114, v114, v114 row_half_mirror row_mask:0xf bank_mask:0xf bound_ctrl:1
	v_add_f32_dpp v115, v115, v115 row_half_mirror row_mask:0xf bank_mask:0xf bound_ctrl:1
	v_add_f32_dpp v116, v116, v116 row_half_mirror row_mask:0xf bank_mask:0xf bound_ctrl:1
	v_add_f32_dpp v117, v117, v117 row_half_mirror row_mask:0xf bank_mask:0xf bound_ctrl:1
	v_add_f32_dpp v118, v118, v118 row_half_mirror row_mask:0xf bank_mask:0xf bound_ctrl:1
	v_add_f32_dpp v119, v119, v119 row_half_mirror row_mask:0xf bank_mask:0xf bound_ctrl:1
	v_add_f32_dpp v104, v104, v104 row_mirror row_mask:0xf bank_mask:0xf bound_ctrl:1
	v_add_f32_dpp v105, v105, v105 row_mirror row_mask:0xf bank_mask:0xf bound_ctrl:1
	v_add_f32_dpp v106, v106, v106 row_mirror row_mask:0xf bank_mask:0xf bound_ctrl:1
	v_add_f32_dpp v107, v107, v107 row_mirror row_mask:0xf bank_mask:0xf bound_ctrl:1
	v_add_f32_dpp v108, v108, v108 row_mirror row_mask:0xf bank_mask:0xf bound_ctrl:1
	v_add_f32_dpp v109, v109, v109 row_mirror row_mask:0xf bank_mask:0xf bound_ctrl:1
	v_add_f32_dpp v110, v110, v110 row_mirror row_mask:0xf bank_mask:0xf bound_ctrl:1
	v_add_f32_dpp v111, v111, v111 row_mirror row_mask:0xf bank_mask:0xf bound_ctrl:1
	v_add_f32_dpp v112, v112, v112 row_mirror row_mask:0xf bank_mask:0xf bound_ctrl:1
	v_add_f32_dpp v113, v113, v113 row_mirror row_mask:0xf bank_mask:0xf bound_ctrl:1
	v_add_f32_dpp v114, v114, v114 row_mirror row_mask:0xf bank_mask:0xf bound_ctrl:1
	v_add_f32_dpp v115, v115, v115 row_mirror row_mask:0xf bank_mask:0xf bound_ctrl:1
	v_add_f32_dpp v116, v116, v116 row_mirror row_mask:0xf bank_mask:0xf bound_ctrl:1
	v_add_f32_dpp v117, v117, v117 row_mirror row_mask:0xf bank_mask:0xf bound_ctrl:1
	v_add_f32_dpp v118, v118, v118 row_mirror row_mask:0xf bank_mask:0xf bound_ctrl:1
	v_add_f32_dpp v119, v119, v119 row_mirror row_mask:0xf bank_mask:0xf bound_ctrl:1
	v_add_u32_e32 v41, s1, v130
	s_xor_b32 s2, s1, 0x4900
	v_add_u32_e32 v39, s2, v128
	v_add_u32_e32 v40, s2, v129
	v_add_u32_e32 v43, s2, v133
	v_add_u32_e32 v142, s2, v134
	v_add_u32_e32 v142, 1088, v142
	v_add_u32_e32 v143, s1, v135
	s_nop 0
	ds_read_b32 v144, v143
	ds_write2_b32 v41, v104, v105 offset0:0 offset1:16
	ds_write2_b32 v41, v106, v107 offset0:32 offset1:48
	ds_write2_b32 v41, v108, v109 offset0:64 offset1:80
	ds_write2_b32 v41, v110, v111 offset0:96 offset1:112
	ds_write2_b32 v41, v112, v113 offset0:128 offset1:144
	ds_write2_b32 v41, v114, v115 offset0:160 offset1:176
	ds_write2_b32 v41, v116, v117 offset0:192 offset1:208
	ds_write2_b32 v41, v118, v119 offset0:224 offset1:240
	s_cmp_eq_u32 s0, 512
	s_cbranch_scc1 .Lgd_noprep
	s_waitcnt vmcnt(0)
	v_lshlrev_b32_e32 v48, 16, v28
	v_and_b32_e32 v49, 0xffff0000, v28
	v_lshlrev_b32_e32 v50, 16, v29
	v_and_b32_e32 v51, 0xffff0000, v29
	v_lshlrev_b32_e32 v52, 16, v30
	v_and_b32_e32 v53, 0xffff0000, v30
	v_lshlrev_b32_e32 v54, 16, v31
	v_and_b32_e32 v55, 0xffff0000, v31
	v_lshlrev_b32_e32 v56, 16, v32
	v_and_b32_e32 v57, 0xffff0000, v32
	v_lshlrev_b32_e32 v58, 16, v33
	v_and_b32_e32 v59, 0xffff0000, v33
	v_lshlrev_b32_e32 v60, 16, v34
	v_and_b32_e32 v61, 0xffff0000, v34
	v_lshlrev_b32_e32 v62, 16, v35
	v_and_b32_e32 v63, 0xffff0000, v35
	v_lshlrev_b32_e32 v64, 16, v36
	v_mov_b32_e32 v65, v37
	ds_write_b128 v39, v[48:51]
	ds_write_b128 v39, v[52:55] offset:16
	v_add_f32_dpp v65, v65, v65 row_shr:1 row_mask:0xf bank_mask:0xf bound_ctrl:1
	ds_write_b128 v39, v[56:59] offset:8192
	ds_write_b128 v39, v[60:63] offset:8208
	v_add_f32_dpp v65, v65, v65 row_shr:2 row_mask:0xf bank_mask:0xf bound_ctrl:1
	v_pk_mul_f32 v[66:67], v[48:49], v[56:57]
	v_pk_fma_f32 v[66:67], v[50:51], v[58:59], v[66:67]
	v_add_f32_dpp v65, v65, v65 row_shr:4 row_mask:0xf bank_mask:0xf bound_ctrl:1
	v_pk_fma_f32 v[66:67], v[52:53], v[60:61], v[66:67]
	v_pk_fma_f32 v[66:67], v[54:55], v[62:63], v[66:67]
	v_add_f32_dpp v65, v65, v65 row_shr:8 row_mask:0xf bank_mask:0xf bound_ctrl:1
	v_add_f32_e32 v68, v66, v67
	ds_write_b32 v40, v64
	v_max_f32_e32 v65, 0xc2a00000, v65
	v_add_f32_dpp v68, v68, v68 quad_perm:[1,0,3,2] row_mask:0xf bank_mask:0xf bound_ctrl:1
	v_mul_f32_e32 v65, 0x3fb8aa3b, v65
	s_nop 0
	v_add_f32_dpp v68, v68, v68 quad_perm:[2,3,0,1] row_mask:0xf bank_mask:0xf bound_ctrl:1
	v_exp_f32_e32 v69, v65
	v_exp_f32_e64 v70, -v65
	v_add_f32_dpp v68, v68, v68 row_half_mirror row_mask:0xf bank_mask:0xf bound_ctrl:1
	s_nop 1
	v_add_f32_dpp v68, v68, v68 row_mirror row_mask:0xf bank_mask:0xf bound_ctrl:1
	v_mul_f32_e32 v23, 0x3db504f3, v69
	v_mul_f32_e32 v21, v38, v70
	v_sub_f32_e32 v20, 0, v69
	ds_write_b32 v43, v68
	ds_write_b32 v142, v23
	s_add_u32 s4, s4, 0xc000
	s_addc_u32 s5, s5, 0
	s_add_u32 s6, s6, 0x200
	s_addc_u32 s7, s7, 0
.Lgd_noprep:
	v_add_u32_e32 v42, s1, v131
	v_add_u32_e32 v10, s2, v45
	v_add_u32_e32 v11, s2, v132
	v_add_u32_e32 v44, s2, v134
	s_waitcnt lgkmcnt(0)
	s_barrier
	ds_read_b32 v120, v42
	ds_read_b32 v22, v44
	ds_read_b128 v[88:91], v11 offset:0
	ds_read_b128 v[92:95], v11 offset:16
	ds_read_b128 v[96:99], v11 offset:32
	ds_read_b128 v[100:103], v11 offset:48
	ds_read_b128 v[48:51], v10 offset:8192
	ds_read_b128 v[52:55], v10 offset:8448
	ds_read_b128 v[56:59], v10
	ds_read_b128 v[60:63], v10 offset:256
	s_waitcnt lgkmcnt(9)
	v_mul_f32_e32 v120, v120, v144
	v_cvt_pk_bf16_f32 v120, v120, v120
	s_waitcnt lgkmcnt(8)
	v_mul_f32_e32 v22, 0x3d800000, v22
	global_store_short v27, v120, s[8:9]
	s_add_u32 s8, s8, 0x8000
	s_addc_u32 s9, s9, 0
	s_mov_b32 s1, s2
	s_add_i32 s0, s0, 1
	s_cmp_lg_u32 s0, 513
	s_cbranch_scc1 .Lgd_chunk
	s_waitcnt lgkmcnt(0)
